# P2 de-phasing: the workgroups that own only two SSD units (first unit < 512, ~25 us of slack) start 13.6 us later
# baseline (speedup 1.0000x reference)
.LBB0_1106:
	s_or_b64 exec, exec, s[0:1]
	s_waitcnt lgkmcnt(0)
	s_barrier
	s_load_dword s33, s[80:81], 0xd0
	v_readlane_b32 s0, v254, 20
	s_sub_i32 s1, 0x2a1, s0
	s_add_u32 s2, s80, 0xd0
	s_addc_u32 s3, s81, 0
	v_writelane_b32 v254, s2, 45
	s_ashr_i32 s0, s1, 31
	s_abs_i32 s1, s1
	v_writelane_b32 v254, s3, 46
	s_waitcnt lgkmcnt(0)
	s_abs_i32 s2, s33
	v_cvt_f32_u32_e32 v2, s2
	s_sub_i32 s3, 0, s2
	s_mov_b32 s93, 0
	v_rcp_iflag_f32_e32 v2, v2
	s_nop 0
	v_mul_f32_e32 v2, 0x4f7ffffe, v2
	v_cvt_u32_f32_e32 v2, v2
	s_nop 0
	v_readfirstlane_b32 s4, v2
	s_mul_i32 s3, s3, s4
	s_mul_hi_u32 s3, s4, s3
	s_add_i32 s4, s4, s3
	s_mul_hi_u32 s3, s1, s4
	s_mul_i32 s3, s3, s2
	s_sub_i32 s1, s1, s3
	s_sub_i32 s3, s1, s2
	s_cmp_ge_u32 s1, s2
	s_cselect_b32 s1, s3, s1
	s_sub_i32 s3, s1, s2
	s_cmp_ge_u32 s1, s2
	s_cselect_b32 s1, s3, s1
	s_xor_b32 s1, s1, s0
	s_sub_i32 s2, s1, s0
	s_cmpk_gt_i32 s2, 0x2a1
	s_cbranch_scc1 .LBB0_1800
	s_sub_i32 s63, 0x2a1, s2
	s_cmpk_gt_u32 s63, 0x1ff
	s_cbranch_scc1 .Lstg2_done
	s_sleep 127
	s_sleep 127
	s_sleep 127
	s_sleep 127
.Lstg2_done:
	s_add_u32 s2, s88, 0x821c000
	s_addc_u32 s3, s89, 0
	v_writelane_b32 v254, s2, 47
	v_mbcnt_hi_u32_b32 v83, -1, v1
	v_bfrev_b32_e32 v85, 0.5
	v_writelane_b32 v254, s3, 48
	s_add_u32 s2, s88, 0x829c000
	v_writelane_b32 v254, s2, 49
	s_addc_u32 s2, s89, 0
	v_writelane_b32 v254, s2, 50
	s_add_u32 s2, s90, 0x1e2ea00
	v_writelane_b32 v254, s2, 51
	s_addc_u32 s2, s91, 0
	v_writelane_b32 v254, s2, 52
	s_add_u32 s2, s90, 0x1880000
	s_addc_u32 s3, s91, 0
	v_writelane_b32 v254, s2, 53
	s_mov_b32 s62, 0xbfb8aa3b
	s_mov_b64 s[66:67], 0x10000
	v_writelane_b32 v254, s3, 54
	s_add_u32 s2, s90, 0x1902000
	s_addc_u32 s3, s91, 0
	v_writelane_b32 v254, s2, 55
	s_movk_i32 s30, 0x1ff
	v_mov_b32_e32 v82, 0x831c000
	v_writelane_b32 v254, s3, 56
	s_add_u32 s2, s90, 0x1984000
	s_addc_u32 s3, s91, 0
	v_writelane_b32 v254, s2, 57
	s_add_u32 s22, s90, 0xa06ea00
	v_mov_b32_e32 v79, 0
	v_writelane_b32 v254, s3, 58
	s_addc_u32 s2, s91, 0
	v_writelane_b32 v254, s2, 59
	s_add_u32 s2, s90, 0x1a26a00
	v_writelane_b32 v254, s2, 60
	s_addc_u32 s2, s91, 0
	s_sub_i32 s0, s0, s1
	s_add_i32 s58, s0, 1
	s_add_u32 s0, s88, 0x8100000
	v_writelane_b32 v254, s2, 61
	s_addc_u32 s1, s89, 0
	v_writelane_b32 v254, s0, 62
	s_mov_b32 s61, 0xc2fc0000
	v_and_b32_e32 v84, 64, v83
	v_writelane_b32 v254, s1, 63
	s_add_i32 s0, 16, 0x2100
	v_writelane_b32 v255, s0, 0
	s_add_i32 s0, 16, 0x17000
	v_writelane_b32 v255, s0, 1
	v_lshl_or_b32 v86, v83, 2, v85
	v_add_u32_e32 v87, -1, v83
	v_add_u32_e32 v88, -2, v83
	v_add_u32_e32 v89, -4, v83
	v_add_u32_e32 v90, -8, v83
	v_add_u32_e32 v91, -16, v83
	v_subrev_u32_e32 v92, 32, v83
	v_mov_b32_e32 v93, 0x80
	v_mov_b32_e32 v94, 0x100
	v_mov_b32_e32 v95, 0x180
	v_mov_b32_e32 v96, 0x200
	v_mov_b32_e32 v97, 0x280
	v_mov_b32_e32 v98, 0x300
	v_mov_b32_e32 v99, 0x380
	v_mov_b32_e32 v100, 16
	v_mov_b32_e32 v101, 0xff800000
	v_mov_b32_e32 v102, 0x42800000
	v_not_b32_e32 v103, 63
	v_mov_b32_e32 v104, 0x7f800000
	v_writelane_b32 v255, s22, 3
	s_branch .LBB0_1109
